# attention branch combine: partner rows (stored write-through sc1) are read with sc1 loads instead of an agent-scope buffer_inv acquire before plain loads (on top of v15)
# baseline (speedup 1.0000x reference)
.LBB0_473:
	s_waitcnt lgkmcnt(0)
	s_nop 0
	s_waitcnt vmcnt(0)
.LBB0_474:
	s_or_b64 exec, exec, s[8:9]
	v_mov_b32_e32 v215, v1
	v_lshl_add_u64 v[2:3], s[58:59], 0, v[214:215]
	v_lshlrev_b32_e32 v0, 10, v99
	s_waitcnt lgkmcnt(0)
	s_barrier
	v_lshl_add_u64 v[6:7], v[2:3], 0, v[0:1]
	global_load_dwordx4 v[2:5], v[6:7], off sc1
	v_lshlrev_b32_e32 v0, 5, v231
	v_lshlrev_b32_e32 v8, 2, v230
	v_lshl_add_u32 v9, v99, 8, v41
	v_lshl_add_u32 v12, v49, 8, v41
	global_load_dwordx4 v[30:33], v0, s[16:17] offset:16
	global_load_dwordx4 v[34:37], v0, s[16:17]
	v_xor_b32_e32 v48, 4, v8
	v_xor_b32_e32 v47, 8, v8
	v_xor_b32_e32 v46, 16, v8
	v_xor_b32_e32 v45, 32, v8
	ds_read_b128 v[8:11], v9
	ds_read_b128 v[50:53], v12
	v_add_co_u32_e32 v12, vcc, 0x1000, v6
	v_xor_b32_e32 v26, 0x80000000, v212
	s_nop 0
	v_addc_co_u32_e32 v13, vcc, 0, v7, vcc
	global_load_dwordx4 v[54:57], v[12:13], off sc1
	v_add_co_u32_e32 v14, vcc, s86, v6
	v_mov_b32_e32 v27, v26
	s_nop 0
	v_addc_co_u32_e32 v15, vcc, 0, v7, vcc
	v_add_co_u32_e32 v12, vcc, 0x3000, v6
	s_waitcnt lgkmcnt(1)
	v_lshlrev_b32_e32 v28, 16, v8
	v_addc_co_u32_e32 v13, vcc, 0, v7, vcc
	global_load_dwordx4 v[22:25], v[14:15], off sc1
	global_load_dwordx4 v[18:21], v[12:13], off sc1
	v_and_b32_e32 v29, 0xffff0000, v8
	v_lshlrev_b32_e32 v8, 16, v9
	v_and_b32_e32 v9, 0xffff0000, v9
	v_lshlrev_b32_e32 v58, 16, v10
	v_and_b32_e32 v59, 0xffff0000, v10
	v_lshlrev_b32_e32 v10, 16, v11
	v_and_b32_e32 v11, 0xffff0000, v11
	s_waitcnt lgkmcnt(0)
	v_lshlrev_b32_e32 v60, 16, v50
	v_and_b32_e32 v61, 0xffff0000, v50
	v_lshlrev_b32_e32 v50, 16, v51
	v_and_b32_e32 v51, 0xffff0000, v51
	v_add_co_u32_e32 v16, vcc, s87, v6
	s_lshl_b64 s[8:9], s[54:55], 11
	s_nop 0
	v_addc_co_u32_e32 v17, vcc, 0, v7, vcc
	v_add_co_u32_e32 v12, vcc, 0x5000, v6
	s_movk_i32 s10, 0x6000
	s_nop 0
	v_addc_co_u32_e32 v13, vcc, 0, v7, vcc
	s_add_u32 s8, s82, s8
	s_addc_u32 s9, s83, s9
	s_waitcnt vmcnt(5)
	v_lshlrev_b32_e32 v14, 16, v2
	v_and_b32_e32 v15, 0xffff0000, v2
	v_lshlrev_b32_e32 v2, 16, v3
	v_and_b32_e32 v3, 0xffff0000, v3
	v_lshlrev_b32_e32 v62, 16, v4
	v_and_b32_e32 v63, 0xffff0000, v4
	v_lshlrev_b32_e32 v4, 16, v5
	v_and_b32_e32 v5, 0xffff0000, v5
	v_pk_fma_f32 v[64:65], v[212:213], v[14:15], v[28:29] neg_lo:[1,0,0] neg_hi:[1,0,0]
	v_pk_fma_f32 v[66:67], v[26:27], v[2:3], v[8:9]
	v_pk_fma_f32 v[58:59], v[212:213], v[62:63], v[58:59] neg_lo:[1,0,0] neg_hi:[1,0,0]
	v_pk_fma_f32 v[62:63], v[26:27], v[4:5], v[10:11]
	v_pk_mul_f32 v[2:3], v[66:67], v[66:67]
	v_pk_mul_f32 v[4:5], v[64:65], v[64:65]
	v_pk_mul_f32 v[8:9], v[62:63], v[62:63]
	v_pk_mul_f32 v[10:11], v[58:59], v[58:59]
	v_pk_mov_b32 v[14:15], v[4:5], v[2:3] op_sel:[1,0]
	v_mov_b32_e32 v5, v3
	v_mov_b32_e32 v2, v8
	v_mov_b32_e32 v3, v10
	v_mov_b32_e32 v10, v9
	v_pk_add_f32 v[4:5], v[14:15], v[4:5]
	v_pk_add_f32 v[2:3], v[2:3], v[10:11]
	v_add_f32_e32 v0, v4, v5
	v_add_f32_e32 v0, v3, v0
	v_add_f32_e32 v0, v2, v0
	ds_bpermute_b32 v3, v48, v0
	s_waitcnt vmcnt(3)
	v_pk_mul_f32 v[28:29], v[34:35], s[52:53] op_sel_hi:[1,0]
	v_pk_mul_f32 v[34:35], v[36:37], s[52:53] op_sel_hi:[1,0]
	s_waitcnt vmcnt(2)
	v_lshlrev_b32_e32 v36, 16, v54
	v_and_b32_e32 v37, 0xffff0000, v54
	s_waitcnt lgkmcnt(0)
	v_add_f32_e32 v0, v0, v3
	ds_bpermute_b32 v5, v47, v0
	v_lshlrev_b32_e32 v54, 16, v55
	v_and_b32_e32 v55, 0xffff0000, v55
	v_pk_fma_f32 v[60:61], v[212:213], v[36:37], v[60:61] neg_lo:[1,0,0] neg_hi:[1,0,0]
	v_pk_fma_f32 v[54:55], v[26:27], v[54:55], v[50:51]
	s_waitcnt lgkmcnt(0)
	v_add_f32_e32 v0, v0, v5
	ds_bpermute_b32 v68, v46, v0
	v_lshlrev_b32_e32 v36, 16, v52
	v_and_b32_e32 v37, 0xffff0000, v52
	v_lshlrev_b32_e32 v50, 16, v53
	v_and_b32_e32 v51, 0xffff0000, v53
	s_waitcnt lgkmcnt(0)
	v_add_f32_e32 v0, v0, v68
	ds_bpermute_b32 v68, v45, v0
	v_lshlrev_b32_e32 v52, 16, v56
	v_and_b32_e32 v53, 0xffff0000, v56
	v_lshlrev_b32_e32 v56, 16, v57
	v_and_b32_e32 v57, 0xffff0000, v57
	s_waitcnt lgkmcnt(0)
	v_add_f32_e32 v0, v0, v68
	v_pk_fma_f32 v[68:69], v[212:213], v[52:53], v[36:37] neg_lo:[1,0,0] neg_hi:[1,0,0]
	v_pk_fma_f32 v[70:71], v[26:27], v[56:57], v[50:51]
	v_pk_mul_f32 v[36:37], v[54:55], v[54:55]
	v_pk_mul_f32 v[50:51], v[60:61], v[60:61]
	v_fmamk_f32 v0, v0, 0x3c000000, v227
	v_pk_mov_b32 v[52:53], v[50:51], v[36:37] op_sel:[1,0]
	v_mov_b32_e32 v51, v37
	v_pk_add_f32 v[36:37], v[52:53], v[50:51]
	v_pk_mul_f32 v[50:51], v[70:71], v[70:71]
	v_pk_mul_f32 v[52:53], v[68:69], v[68:69]
	v_mov_b32_e32 v56, v50
	v_mov_b32_e32 v57, v52
	v_mov_b32_e32 v52, v51
	v_pk_add_f32 v[50:51], v[56:57], v[52:53]
	v_add_f32_e32 v36, v36, v37
	v_add_f32_e32 v36, v51, v36
	v_add_f32_e32 v56, v50, v36
	ds_bpermute_b32 v57, v48, v56
	v_rsq_f32_e32 v0, v0
	global_load_dwordx4 v[14:17], v[16:17], off sc1
	s_nop 0
	global_load_dwordx4 v[10:13], v[12:13], off sc1
	v_add_co_u32_e32 v2, vcc, s10, v6
	v_pk_mul_f32 v[50:51], v[64:65], v[0:1] op_sel_hi:[1,0]
	s_waitcnt lgkmcnt(0)
	v_add_f32_e32 v64, v56, v57
	ds_bpermute_b32 v65, v47, v64
	v_pk_mul_f32 v[52:53], v[66:67], v[0:1] op_sel_hi:[1,0]
	v_pk_mul_f32 v[56:57], v[58:59], v[0:1] op_sel_hi:[1,0]
	v_pk_mul_f32 v[58:59], v[62:63], v[0:1] op_sel_hi:[1,0]
	v_addc_co_u32_e32 v3, vcc, 0, v7, vcc
	s_waitcnt lgkmcnt(0)
	v_add_f32_e32 v0, v64, v65
	ds_bpermute_b32 v62, v46, v0
	v_pk_mul_f32 v[30:31], v[30:31], s[52:53] op_sel_hi:[1,0]
	v_pk_mul_f32 v[32:33], v[32:33], s[52:53] op_sel_hi:[1,0]
	v_add_co_u32_e32 v4, vcc, 0x7000, v6
	s_waitcnt lgkmcnt(0)
	v_add_f32_e32 v62, v0, v62
	ds_bpermute_b32 v63, v45, v62
	v_lshl_add_u64 v[36:37], s[8:9], 0, v[214:215]
	v_pk_mul_f32 v[52:53], v[34:35], v[52:53]
	v_pk_mul_f32 v[50:51], v[28:29], v[50:51]
	v_pk_mul_f32 v[58:59], v[32:33], v[58:59]
	v_pk_mul_f32 v[56:57], v[30:31], v[56:57]
	v_lshlrev_b32_e32 v0, 11, v99
	v_addc_co_u32_e32 v5, vcc, 0, v7, vcc
	v_cvt_pk_bf16_f32 v50, v50, v51
	v_cvt_pk_bf16_f32 v51, v52, v53
	v_cvt_pk_bf16_f32 v52, v56, v57
	v_cvt_pk_bf16_f32 v53, v58, v59
	v_lshl_add_u64 v[56:57], v[36:37], 0, v[0:1]
	s_waitcnt lgkmcnt(0)
	v_add_f32_e32 v0, v62, v63
	global_load_dwordx4 v[6:9], v[2:3], off sc1
	s_nop 0
	global_load_dwordx4 v[2:5], v[4:5], off sc1
	v_fmamk_f32 v0, v0, 0x3c000000, v227
	global_store_dwordx4 v[56:57], v[50:53], off
	v_rsq_f32_e32 v0, v0
	s_waitcnt vmcnt(6)
	v_lshlrev_b32_e32 v64, 16, v22
	v_lshl_add_u32 v50, v44, 8, v41
	ds_read_b128 v[50:53], v50
	v_pk_mul_f32 v[58:59], v[60:61], v[0:1] op_sel_hi:[1,0]
	v_pk_mul_f32 v[60:61], v[54:55], v[0:1] op_sel_hi:[1,0]
	v_lshl_add_u32 v54, v43, 8, v41
	ds_read_b128 v[54:57], v54
	s_waitcnt lgkmcnt(1)
	v_lshlrev_b32_e32 v62, 16, v50
	v_and_b32_e32 v63, 0xffff0000, v50
	v_lshlrev_b32_e32 v50, 16, v51
	v_and_b32_e32 v51, 0xffff0000, v51
	v_and_b32_e32 v65, 0xffff0000, v22
	v_lshlrev_b32_e32 v22, 16, v23
	v_and_b32_e32 v23, 0xffff0000, v23
	v_pk_fma_f32 v[62:63], v[212:213], v[64:65], v[62:63] neg_lo:[1,0,0] neg_hi:[1,0,0]
	v_pk_fma_f32 v[50:51], v[26:27], v[22:23], v[50:51]
	v_lshlrev_b32_e32 v22, 16, v52
	v_and_b32_e32 v23, 0xffff0000, v52
	v_lshlrev_b32_e32 v52, 16, v53
	v_and_b32_e32 v53, 0xffff0000, v53
	v_lshlrev_b32_e32 v64, 16, v24
	v_and_b32_e32 v65, 0xffff0000, v24
	v_lshlrev_b32_e32 v24, 16, v25
	v_and_b32_e32 v25, 0xffff0000, v25
	v_pk_fma_f32 v[64:65], v[212:213], v[64:65], v[22:23] neg_lo:[1,0,0] neg_hi:[1,0,0]
	v_pk_fma_f32 v[52:53], v[26:27], v[24:25], v[52:53]
	v_pk_mul_f32 v[22:23], v[50:51], v[50:51]
	v_pk_mul_f32 v[24:25], v[62:63], v[62:63]
	s_nop 0
	v_pk_mov_b32 v[66:67], v[24:25], v[22:23] op_sel:[1,0]
	v_mov_b32_e32 v25, v23
	v_pk_add_f32 v[22:23], v[66:67], v[24:25]
	v_pk_mul_f32 v[24:25], v[52:53], v[52:53]
	v_pk_mul_f32 v[66:67], v[64:65], v[64:65]
	v_mov_b32_e32 v72, v24
	v_mov_b32_e32 v73, v66
	v_mov_b32_e32 v66, v25
	v_pk_add_f32 v[24:25], v[72:73], v[66:67]
	v_add_f32_e32 v22, v22, v23
	v_add_f32_e32 v22, v25, v22
	v_add_f32_e32 v66, v24, v22
	ds_bpermute_b32 v67, v48, v66
	v_pk_mul_f32 v[24:25], v[34:35], v[60:61]
	v_pk_mul_f32 v[22:23], v[28:29], v[58:59]
	v_pk_mul_f32 v[58:59], v[68:69], v[0:1] op_sel_hi:[1,0]
	v_pk_mul_f32 v[60:61], v[70:71], v[0:1] op_sel_hi:[1,0]
	s_waitcnt lgkmcnt(0)
	v_add_f32_e32 v0, v66, v67
	ds_bpermute_b32 v66, v47, v0
	v_pk_mul_f32 v[60:61], v[32:33], v[60:61]
	v_pk_mul_f32 v[58:59], v[30:31], v[58:59]
	v_cvt_pk_bf16_f32 v22, v22, v23
	v_cvt_pk_bf16_f32 v23, v24, v25
	s_waitcnt lgkmcnt(0)
	v_add_f32_e32 v66, v0, v66
	ds_bpermute_b32 v67, v46, v66
	v_lshlrev_b32_e32 v0, 11, v49
	v_cvt_pk_bf16_f32 v24, v58, v59
	v_cvt_pk_bf16_f32 v25, v60, v61
	v_lshl_add_u64 v[58:59], v[36:37], 0, v[0:1]
	s_waitcnt lgkmcnt(0)
	v_add_f32_e32 v0, v66, v67
	v_lshlrev_b32_e32 v60, 16, v54
	v_and_b32_e32 v61, 0xffff0000, v54
	v_lshlrev_b32_e32 v54, 16, v55
	v_and_b32_e32 v55, 0xffff0000, v55
	s_waitcnt vmcnt(5)
	v_lshlrev_b32_e32 v66, 16, v18
	v_and_b32_e32 v67, 0xffff0000, v18
	v_lshlrev_b32_e32 v18, 16, v19
	v_and_b32_e32 v19, 0xffff0000, v19
	v_pk_fma_f32 v[60:61], v[212:213], v[66:67], v[60:61] neg_lo:[1,0,0] neg_hi:[1,0,0]
	v_pk_fma_f32 v[54:55], v[26:27], v[18:19], v[54:55]
	v_lshlrev_b32_e32 v18, 16, v56
	v_and_b32_e32 v19, 0xffff0000, v56
	v_lshlrev_b32_e32 v56, 16, v57
	v_and_b32_e32 v57, 0xffff0000, v57
	v_lshlrev_b32_e32 v66, 16, v20
	v_and_b32_e32 v67, 0xffff0000, v20
	v_lshlrev_b32_e32 v20, 16, v21
	v_and_b32_e32 v21, 0xffff0000, v21
	v_pk_fma_f32 v[66:67], v[212:213], v[66:67], v[18:19] neg_lo:[1,0,0] neg_hi:[1,0,0]
	v_pk_fma_f32 v[56:57], v[26:27], v[20:21], v[56:57]
	v_pk_mul_f32 v[18:19], v[54:55], v[54:55]
	v_pk_mul_f32 v[20:21], v[60:61], v[60:61]
	ds_bpermute_b32 v49, v45, v0
	v_pk_mov_b32 v[68:69], v[20:21], v[18:19] op_sel:[1,0]
	v_mov_b32_e32 v21, v19
	v_pk_add_f32 v[18:19], v[68:69], v[20:21]
	v_pk_mul_f32 v[20:21], v[56:57], v[56:57]
	v_pk_mul_f32 v[68:69], v[66:67], v[66:67]
	v_mov_b32_e32 v70, v20
	v_mov_b32_e32 v71, v68
	v_mov_b32_e32 v68, v21
	v_pk_add_f32 v[20:21], v[70:71], v[68:69]
	v_add_f32_e32 v18, v18, v19
	v_add_f32_e32 v18, v21, v18
	v_add_f32_e32 v18, v20, v18
	ds_bpermute_b32 v19, v48, v18
	global_store_dwordx4 v[58:59], v[22:25], off
	s_waitcnt lgkmcnt(1)
	v_add_f32_e32 v0, v0, v49
	v_fmamk_f32 v0, v0, 0x3c000000, v227
	v_rsq_f32_e32 v0, v0
	s_waitcnt lgkmcnt(0)
	v_add_f32_e32 v22, v18, v19
	ds_bpermute_b32 v23, v47, v22
	v_pk_mul_f32 v[20:21], v[50:51], v[0:1] op_sel_hi:[1,0]
	v_pk_mul_f32 v[18:19], v[62:63], v[0:1] op_sel_hi:[1,0]
	v_pk_mul_f32 v[24:25], v[52:53], v[0:1] op_sel_hi:[1,0]
	s_waitcnt lgkmcnt(0)
	v_add_f32_e32 v49, v22, v23
	ds_bpermute_b32 v50, v46, v49
	v_pk_mul_f32 v[22:23], v[64:65], v[0:1] op_sel_hi:[1,0]
	v_pk_mul_f32 v[20:21], v[34:35], v[20:21]
	v_pk_mul_f32 v[18:19], v[28:29], v[18:19]
	v_pk_mul_f32 v[22:23], v[30:31], v[22:23]
	s_waitcnt lgkmcnt(0)
	v_add_f32_e32 v0, v49, v50
	ds_bpermute_b32 v49, v45, v0
	v_pk_mul_f32 v[24:25], v[32:33], v[24:25]
	v_cvt_pk_bf16_f32 v18, v18, v19
	v_cvt_pk_bf16_f32 v19, v20, v21
	v_cvt_pk_bf16_f32 v20, v22, v23
	v_lshl_add_u32 v22, v42, 8, v41
	v_cvt_pk_bf16_f32 v21, v24, v25
	ds_read_b128 v[22:25], v22
	s_waitcnt lgkmcnt(1)
	v_add_f32_e32 v0, v0, v49
	v_fmamk_f32 v0, v0, 0x3c000000, v227
	v_rsq_f32_e32 v58, v0
	v_lshl_add_u32 v0, v40, 8, v41
	ds_read_b128 v[50:53], v0
	s_waitcnt lgkmcnt(1)
	v_lshlrev_b32_e32 v62, 16, v22
	v_and_b32_e32 v63, 0xffff0000, v22
	v_lshlrev_b32_e32 v22, 16, v23
	v_and_b32_e32 v23, 0xffff0000, v23
	s_waitcnt vmcnt(5)
	v_lshlrev_b32_e32 v64, 16, v14
	v_and_b32_e32 v65, 0xffff0000, v14
	v_lshlrev_b32_e32 v14, 16, v15
	v_and_b32_e32 v15, 0xffff0000, v15
	v_pk_fma_f32 v[62:63], v[212:213], v[64:65], v[62:63] neg_lo:[1,0,0] neg_hi:[1,0,0]
	v_pk_fma_f32 v[22:23], v[26:27], v[14:15], v[22:23]
	v_lshlrev_b32_e32 v14, 16, v24
	v_and_b32_e32 v15, 0xffff0000, v24
	v_lshlrev_b32_e32 v24, 16, v25
	v_and_b32_e32 v25, 0xffff0000, v25
	v_lshlrev_b32_e32 v64, 16, v16
	v_and_b32_e32 v65, 0xffff0000, v16
	v_lshlrev_b32_e32 v16, 16, v17
	v_and_b32_e32 v17, 0xffff0000, v17
	v_pk_fma_f32 v[64:65], v[212:213], v[64:65], v[14:15] neg_lo:[1,0,0] neg_hi:[1,0,0]
	v_pk_fma_f32 v[24:25], v[26:27], v[16:17], v[24:25]
	v_pk_mul_f32 v[14:15], v[22:23], v[22:23]
	v_pk_mul_f32 v[16:17], v[62:63], v[62:63]
	s_nop 0
	v_pk_mov_b32 v[68:69], v[16:17], v[14:15] op_sel:[1,0]
	v_mov_b32_e32 v17, v15
	v_pk_add_f32 v[14:15], v[68:69], v[16:17]
	v_pk_mul_f32 v[16:17], v[24:25], v[24:25]
	v_pk_mul_f32 v[68:69], v[64:65], v[64:65]
	v_mov_b32_e32 v70, v16
	v_mov_b32_e32 v71, v68
	v_mov_b32_e32 v68, v17
	v_pk_add_f32 v[16:17], v[70:71], v[68:69]
	v_add_f32_e32 v0, v14, v15
	v_add_f32_e32 v0, v17, v0
	v_add_f32_e32 v16, v16, v0
	ds_bpermute_b32 v17, v48, v16
	v_lshlrev_b32_e32 v0, 11, v44
	v_lshl_add_u64 v[14:15], v[36:37], 0, v[0:1]
	global_store_dwordx4 v[14:15], v[18:21], off
	v_pk_mul_f32 v[14:15], v[60:61], v[58:59] op_sel_hi:[1,0]
	s_waitcnt lgkmcnt(0)
	v_add_f32_e32 v0, v16, v17
	ds_bpermute_b32 v20, v47, v0
	v_pk_mul_f32 v[16:17], v[54:55], v[58:59] op_sel_hi:[1,0]
	v_pk_mul_f32 v[14:15], v[28:29], v[14:15]
	v_pk_mul_f32 v[16:17], v[34:35], v[16:17]
	v_cvt_pk_bf16_f32 v14, v14, v15
	s_waitcnt lgkmcnt(0)
	v_add_f32_e32 v0, v0, v20
	ds_bpermute_b32 v44, v46, v0
	v_pk_mul_f32 v[20:21], v[56:57], v[58:59] op_sel_hi:[1,0]
	v_cvt_pk_bf16_f32 v15, v16, v17
	v_pk_mul_f32 v[20:21], v[32:33], v[20:21]
	s_waitcnt vmcnt(5)
	v_lshlrev_b32_e32 v54, 16, v10
	v_cvt_pk_bf16_f32 v17, v20, v21
	v_lshlrev_b32_e32 v20, 16, v50
	v_and_b32_e32 v21, 0xffff0000, v50
	v_lshlrev_b32_e32 v50, 16, v51
	v_and_b32_e32 v51, 0xffff0000, v51
	v_and_b32_e32 v55, 0xffff0000, v10
	v_lshlrev_b32_e32 v10, 16, v11
	v_and_b32_e32 v11, 0xffff0000, v11
	v_pk_fma_f32 v[20:21], v[212:213], v[54:55], v[20:21] neg_lo:[1,0,0] neg_hi:[1,0,0]
	v_pk_fma_f32 v[50:51], v[26:27], v[10:11], v[50:51]
	v_lshlrev_b32_e32 v10, 16, v52
	v_and_b32_e32 v11, 0xffff0000, v52
	v_lshlrev_b32_e32 v52, 16, v53
	v_and_b32_e32 v53, 0xffff0000, v53
	v_lshlrev_b32_e32 v54, 16, v12
	v_and_b32_e32 v55, 0xffff0000, v12
	v_lshlrev_b32_e32 v12, 16, v13
	v_and_b32_e32 v13, 0xffff0000, v13
	v_pk_fma_f32 v[54:55], v[212:213], v[54:55], v[10:11] neg_lo:[1,0,0] neg_hi:[1,0,0]
	v_pk_fma_f32 v[52:53], v[26:27], v[12:13], v[52:53]
	v_pk_mul_f32 v[10:11], v[50:51], v[50:51]
	v_pk_mul_f32 v[12:13], v[20:21], v[20:21]
	s_waitcnt lgkmcnt(0)
	v_add_f32_e32 v44, v0, v44
	v_pk_mov_b32 v[56:57], v[12:13], v[10:11] op_sel:[1,0]
	v_mov_b32_e32 v13, v11
	ds_bpermute_b32 v49, v45, v44
	v_pk_add_f32 v[10:11], v[56:57], v[12:13]
	v_pk_mul_f32 v[12:13], v[52:53], v[52:53]
	v_pk_mul_f32 v[56:57], v[54:55], v[54:55]
	v_pk_mul_f32 v[18:19], v[66:67], v[58:59] op_sel_hi:[1,0]
	v_mov_b32_e32 v58, v12
	v_mov_b32_e32 v59, v56
	v_mov_b32_e32 v56, v13
	v_pk_add_f32 v[12:13], v[58:59], v[56:57]
	v_add_f32_e32 v10, v10, v11
	v_pk_mul_f32 v[18:19], v[30:31], v[18:19]
	v_add_f32_e32 v10, v13, v10
	v_cvt_pk_bf16_f32 v16, v18, v19
	v_add_f32_e32 v19, v12, v10
	v_lshlrev_b32_e32 v0, 11, v43
	s_waitcnt lgkmcnt(0)
	v_add_f32_e32 v18, v44, v49
	ds_bpermute_b32 v43, v48, v19
	v_fmamk_f32 v18, v18, 0x3c000000, v227
	v_rsq_f32_e32 v18, v18
	v_lshl_add_u64 v[10:11], v[36:37], 0, v[0:1]
	global_store_dwordx4 v[10:11], v[14:17], off
	s_waitcnt lgkmcnt(0)
	v_add_f32_e32 v0, v19, v43
	v_pk_mul_f32 v[10:11], v[62:63], v[18:19] op_sel_hi:[1,0]
	v_pk_mul_f32 v[12:13], v[22:23], v[18:19] op_sel_hi:[1,0]
	ds_bpermute_b32 v19, v47, v0
	v_pk_mul_f32 v[12:13], v[34:35], v[12:13]
	v_pk_mul_f32 v[10:11], v[28:29], v[10:11]
	s_waitcnt lgkmcnt(0)
	v_add_f32_e32 v0, v0, v19
	v_pk_mul_f32 v[14:15], v[64:65], v[18:19] op_sel_hi:[1,0]
	v_pk_mul_f32 v[16:17], v[24:25], v[18:19] op_sel_hi:[1,0]
	ds_bpermute_b32 v18, v46, v0
	v_pk_mul_f32 v[16:17], v[32:33], v[16:17]
	v_pk_mul_f32 v[14:15], v[30:31], v[14:15]
	v_cvt_pk_bf16_f32 v10, v10, v11
	v_cvt_pk_bf16_f32 v11, v12, v13
	s_waitcnt lgkmcnt(0)
	v_add_f32_e32 v18, v0, v18
	v_lshlrev_b32_e32 v0, 11, v42
	v_cvt_pk_bf16_f32 v12, v14, v15
	v_cvt_pk_bf16_f32 v13, v16, v17
	v_lshl_add_u64 v[14:15], v[36:37], 0, v[0:1]
	ds_bpermute_b32 v19, v45, v18
	global_store_dwordx4 v[14:15], v[10:13], off
	v_lshl_add_u32 v14, v38, 8, v41
	ds_read_b128 v[14:17], v14
	v_lshl_add_u32 v10, v39, 8, v41
	ds_read_b128 v[10:13], v10
	s_waitcnt lgkmcnt(2)
	v_add_f32_e32 v0, v18, v19
	v_fmamk_f32 v0, v0, 0x3c000000, v227
	s_waitcnt vmcnt(6)
	v_lshlrev_b32_e32 v24, 16, v6
	v_and_b32_e32 v25, 0xffff0000, v6
	s_waitcnt lgkmcnt(0)
	v_lshlrev_b32_e32 v22, 16, v10
	v_and_b32_e32 v23, 0xffff0000, v10
	v_lshlrev_b32_e32 v10, 16, v11
	v_and_b32_e32 v11, 0xffff0000, v11
	v_lshlrev_b32_e32 v6, 16, v7
	v_and_b32_e32 v7, 0xffff0000, v7
	v_rsq_f32_e32 v0, v0
	v_pk_fma_f32 v[22:23], v[212:213], v[24:25], v[22:23] neg_lo:[1,0,0] neg_hi:[1,0,0]
	v_pk_fma_f32 v[10:11], v[26:27], v[6:7], v[10:11]
	v_lshlrev_b32_e32 v6, 16, v12
	v_and_b32_e32 v7, 0xffff0000, v12
	v_lshlrev_b32_e32 v12, 16, v13
	v_and_b32_e32 v13, 0xffff0000, v13
	v_lshlrev_b32_e32 v24, 16, v8
	v_and_b32_e32 v25, 0xffff0000, v8
	v_lshlrev_b32_e32 v8, 16, v9
	v_and_b32_e32 v9, 0xffff0000, v9
	v_pk_fma_f32 v[24:25], v[212:213], v[24:25], v[6:7] neg_lo:[1,0,0] neg_hi:[1,0,0]
	v_pk_fma_f32 v[12:13], v[26:27], v[8:9], v[12:13]
	v_pk_mul_f32 v[6:7], v[10:11], v[10:11]
	v_pk_mul_f32 v[8:9], v[22:23], v[22:23]
	v_pk_mul_f32 v[18:19], v[20:21], v[0:1] op_sel_hi:[1,0]
	v_pk_mov_b32 v[42:43], v[8:9], v[6:7] op_sel:[1,0]
	v_mov_b32_e32 v9, v7
	v_pk_add_f32 v[6:7], v[42:43], v[8:9]
	v_pk_mul_f32 v[8:9], v[12:13], v[12:13]
	v_pk_mul_f32 v[42:43], v[24:25], v[24:25]
	v_pk_mul_f32 v[20:21], v[50:51], v[0:1] op_sel_hi:[1,0]
	v_mov_b32_e32 v50, v8
	v_mov_b32_e32 v51, v42
	v_mov_b32_e32 v42, v9
	v_pk_add_f32 v[8:9], v[50:51], v[42:43]
	v_add_f32_e32 v6, v6, v7
	v_add_f32_e32 v6, v9, v6
	v_add_f32_e32 v41, v8, v6
	ds_bpermute_b32 v42, v48, v41
	v_pk_mul_f32 v[8:9], v[34:35], v[20:21]
	v_pk_mul_f32 v[6:7], v[28:29], v[18:19]
	v_pk_mul_f32 v[18:19], v[54:55], v[0:1] op_sel_hi:[1,0]
	v_pk_mul_f32 v[20:21], v[52:53], v[0:1] op_sel_hi:[1,0]
	s_waitcnt lgkmcnt(0)
	v_add_f32_e32 v0, v41, v42
	ds_bpermute_b32 v41, v47, v0
	v_pk_mul_f32 v[20:21], v[32:33], v[20:21]
	v_pk_mul_f32 v[18:19], v[30:31], v[18:19]
	v_cvt_pk_bf16_f32 v6, v6, v7
	v_cvt_pk_bf16_f32 v7, v8, v9
	s_waitcnt lgkmcnt(0)
	v_add_f32_e32 v41, v0, v41
	ds_bpermute_b32 v42, v46, v41
	v_lshlrev_b32_e32 v0, 11, v40
	v_cvt_pk_bf16_f32 v8, v18, v19
	v_cvt_pk_bf16_f32 v9, v20, v21
	v_lshl_add_u64 v[18:19], v[36:37], 0, v[0:1]
	s_waitcnt lgkmcnt(0)
	v_add_f32_e32 v0, v41, v42
	v_lshlrev_b32_e32 v20, 16, v14
	v_and_b32_e32 v21, 0xffff0000, v14
	v_lshlrev_b32_e32 v14, 16, v15
	v_and_b32_e32 v15, 0xffff0000, v15
	s_waitcnt vmcnt(5)
	v_lshlrev_b32_e32 v40, 16, v2
	v_and_b32_e32 v41, 0xffff0000, v2
	v_lshlrev_b32_e32 v2, 16, v3
	v_and_b32_e32 v3, 0xffff0000, v3
	v_pk_fma_f32 v[20:21], v[212:213], v[40:41], v[20:21] neg_lo:[1,0,0] neg_hi:[1,0,0]
	v_pk_fma_f32 v[14:15], v[26:27], v[2:3], v[14:15]
	v_lshlrev_b32_e32 v2, 16, v16
	v_and_b32_e32 v3, 0xffff0000, v16
	v_lshlrev_b32_e32 v16, 16, v17
	v_and_b32_e32 v17, 0xffff0000, v17
	v_lshlrev_b32_e32 v40, 16, v4
	v_and_b32_e32 v41, 0xffff0000, v4
	v_lshlrev_b32_e32 v4, 16, v5
	v_and_b32_e32 v5, 0xffff0000, v5
	v_pk_fma_f32 v[40:41], v[212:213], v[40:41], v[2:3] neg_lo:[1,0,0] neg_hi:[1,0,0]
	v_pk_fma_f32 v[16:17], v[26:27], v[4:5], v[16:17]
	v_pk_mul_f32 v[2:3], v[14:15], v[14:15]
	v_pk_mul_f32 v[4:5], v[20:21], v[20:21]
	ds_bpermute_b32 v44, v45, v0
	v_pk_mov_b32 v[26:27], v[4:5], v[2:3] op_sel:[1,0]
	v_mov_b32_e32 v5, v3
	v_pk_add_f32 v[2:3], v[26:27], v[4:5]
	v_pk_mul_f32 v[4:5], v[16:17], v[16:17]
	v_pk_mul_f32 v[26:27], v[40:41], v[40:41]
	v_mov_b32_e32 v42, v4
	v_mov_b32_e32 v43, v26
	v_mov_b32_e32 v26, v5
	v_pk_add_f32 v[4:5], v[42:43], v[26:27]
	v_add_f32_e32 v2, v2, v3
	v_add_f32_e32 v2, v5, v2
	v_add_f32_e32 v2, v4, v2
	ds_bpermute_b32 v3, v48, v2
	s_waitcnt lgkmcnt(1)
	v_add_f32_e32 v0, v0, v44
	global_store_dwordx4 v[18:19], v[6:9], off
	v_fmamk_f32 v0, v0, 0x3c000000, v227
	v_rsq_f32_e32 v0, v0
	s_waitcnt lgkmcnt(0)
	v_add_f32_e32 v6, v2, v3
	ds_bpermute_b32 v7, v47, v6
	v_pk_mul_f32 v[4:5], v[10:11], v[0:1] op_sel_hi:[1,0]
	v_pk_mul_f32 v[2:3], v[22:23], v[0:1] op_sel_hi:[1,0]
	v_pk_mul_f32 v[8:9], v[12:13], v[0:1] op_sel_hi:[1,0]
	s_waitcnt lgkmcnt(0)
	v_add_f32_e32 v10, v6, v7
	ds_bpermute_b32 v11, v46, v10
	v_pk_mul_f32 v[6:7], v[24:25], v[0:1] op_sel_hi:[1,0]
	v_pk_mul_f32 v[4:5], v[34:35], v[4:5]
	v_pk_mul_f32 v[2:3], v[28:29], v[2:3]
	v_pk_mul_f32 v[6:7], v[30:31], v[6:7]
	s_waitcnt lgkmcnt(0)
	v_add_f32_e32 v0, v10, v11
	ds_bpermute_b32 v10, v45, v0
	v_cvt_pk_bf16_f32 v2, v2, v3
	v_cvt_pk_bf16_f32 v3, v4, v5
	v_cvt_pk_bf16_f32 v4, v6, v7
	v_pk_mul_f32 v[8:9], v[32:33], v[8:9]
	s_waitcnt lgkmcnt(0)
	v_add_f32_e32 v0, v0, v10
	v_fmamk_f32 v0, v0, 0x3c000000, v227
	v_rsq_f32_e32 v6, v0
	v_lshlrev_b32_e32 v0, 11, v39
	v_cvt_pk_bf16_f32 v5, v8, v9
	v_lshl_add_u64 v[8:9], v[36:37], 0, v[0:1]
	global_store_dwordx4 v[8:9], v[2:5], off
	v_pk_mul_f32 v[8:9], v[40:41], v[6:7] op_sel_hi:[1,0]
	v_lshlrev_b32_e32 v0, 11, v38
	v_pk_mul_f32 v[2:3], v[20:21], v[6:7] op_sel_hi:[1,0]
	v_pk_mul_f32 v[4:5], v[14:15], v[6:7] op_sel_hi:[1,0]
	v_pk_mul_f32 v[6:7], v[16:17], v[6:7] op_sel_hi:[1,0]
	v_pk_mul_f32 v[4:5], v[34:35], v[4:5]
	v_pk_mul_f32 v[2:3], v[28:29], v[2:3]
	v_pk_mul_f32 v[6:7], v[32:33], v[6:7]
	v_pk_mul_f32 v[8:9], v[30:31], v[8:9]
	v_cvt_pk_bf16_f32 v2, v2, v3
	v_cvt_pk_bf16_f32 v3, v4, v5
	v_cvt_pk_bf16_f32 v4, v8, v9
	v_cvt_pk_bf16_f32 v5, v6, v7
	v_lshl_add_u64 v[6:7], v[36:37], 0, v[0:1]
	global_store_dwordx4 v[6:7], v[2:5], off
	s_waitcnt lgkmcnt(0)
	s_barrier

.LBB0_1344:
	s_or_b64 exec, exec, s[10:11]
	v_mov_b32_e32 v215, v1
	v_lshl_add_u64 v[2:3], s[58:59], 0, v[214:215]
	v_lshlrev_b32_e32 v0, 10, v99
	s_waitcnt lgkmcnt(0)
	s_barrier
	v_lshl_add_u64 v[6:7], v[2:3], 0, v[0:1]
	global_load_dwordx4 v[2:5], v[6:7], off sc1
	v_lshlrev_b32_e32 v0, 5, v231
	v_lshlrev_b32_e32 v8, 2, v230
	v_lshl_add_u32 v9, v99, 8, v41
	v_lshl_add_u32 v12, v49, 8, v41
	global_load_dwordx4 v[30:33], v0, s[16:17] offset:528
	global_load_dwordx4 v[34:37], v0, s[16:17] offset:512
	v_xor_b32_e32 v48, 4, v8
	v_xor_b32_e32 v47, 8, v8
	v_xor_b32_e32 v46, 16, v8
	v_xor_b32_e32 v45, 32, v8
	ds_read_b128 v[8:11], v9
	ds_read_b128 v[50:53], v12
	v_add_co_u32_e32 v12, vcc, 0x1000, v6
	v_xor_b32_e32 v26, 0x80000000, v212
	s_nop 0
	v_addc_co_u32_e32 v13, vcc, 0, v7, vcc
	global_load_dwordx4 v[54:57], v[12:13], off sc1
	v_add_co_u32_e32 v14, vcc, 0x2000, v6
	v_mov_b32_e32 v27, v26
	s_nop 0
	v_addc_co_u32_e32 v15, vcc, 0, v7, vcc
	v_add_co_u32_e32 v12, vcc, 0x3000, v6
	s_waitcnt lgkmcnt(1)
	v_lshlrev_b32_e32 v28, 16, v8
	v_addc_co_u32_e32 v13, vcc, 0, v7, vcc
	global_load_dwordx4 v[22:25], v[14:15], off sc1
	global_load_dwordx4 v[18:21], v[12:13], off sc1
	v_and_b32_e32 v29, 0xffff0000, v8
	v_lshlrev_b32_e32 v8, 16, v9
	v_and_b32_e32 v9, 0xffff0000, v9
	v_lshlrev_b32_e32 v58, 16, v10
	v_and_b32_e32 v59, 0xffff0000, v10
	v_lshlrev_b32_e32 v10, 16, v11
	v_and_b32_e32 v11, 0xffff0000, v11
	s_waitcnt lgkmcnt(0)
	v_lshlrev_b32_e32 v60, 16, v50
	v_and_b32_e32 v61, 0xffff0000, v50
	v_lshlrev_b32_e32 v50, 16, v51
	v_and_b32_e32 v51, 0xffff0000, v51
	v_add_co_u32_e32 v16, vcc, 0x4000, v6
	s_lshl_b64 s[10:11], s[52:53], 11
	s_nop 0
	v_addc_co_u32_e32 v17, vcc, 0, v7, vcc
	v_add_co_u32_e32 v12, vcc, 0x5000, v6
	s_movk_i32 s12, 0x6000
	s_nop 0
	v_addc_co_u32_e32 v13, vcc, 0, v7, vcc
	s_add_u32 s10, s83, s10
	s_addc_u32 s11, s84, s11
	s_waitcnt vmcnt(5)
	v_lshlrev_b32_e32 v14, 16, v2
	v_and_b32_e32 v15, 0xffff0000, v2
	v_lshlrev_b32_e32 v2, 16, v3
	v_and_b32_e32 v3, 0xffff0000, v3
	v_lshlrev_b32_e32 v62, 16, v4
	v_and_b32_e32 v63, 0xffff0000, v4
	v_lshlrev_b32_e32 v4, 16, v5
	v_and_b32_e32 v5, 0xffff0000, v5
	v_pk_fma_f32 v[64:65], v[212:213], v[14:15], v[28:29] neg_lo:[1,0,0] neg_hi:[1,0,0]
	v_pk_fma_f32 v[66:67], v[26:27], v[2:3], v[8:9]
	v_pk_fma_f32 v[58:59], v[212:213], v[62:63], v[58:59] neg_lo:[1,0,0] neg_hi:[1,0,0]
	v_pk_fma_f32 v[62:63], v[26:27], v[4:5], v[10:11]
	v_pk_mul_f32 v[2:3], v[66:67], v[66:67]
	v_pk_mul_f32 v[4:5], v[64:65], v[64:65]
	v_pk_mul_f32 v[8:9], v[62:63], v[62:63]
	v_pk_mul_f32 v[10:11], v[58:59], v[58:59]
	v_pk_mov_b32 v[14:15], v[4:5], v[2:3] op_sel:[1,0]
	v_mov_b32_e32 v5, v3
	v_mov_b32_e32 v2, v8
	v_mov_b32_e32 v3, v10
	v_mov_b32_e32 v10, v9
	v_pk_add_f32 v[4:5], v[14:15], v[4:5]
	v_pk_add_f32 v[2:3], v[2:3], v[10:11]
	v_add_f32_e32 v0, v4, v5
	v_add_f32_e32 v0, v3, v0
	v_add_f32_e32 v0, v2, v0
	ds_bpermute_b32 v3, v48, v0
	s_waitcnt vmcnt(3)
	v_pk_mul_f32 v[28:29], v[34:35], s[50:51] op_sel_hi:[1,0]
	v_pk_mul_f32 v[34:35], v[36:37], s[50:51] op_sel_hi:[1,0]
	s_waitcnt vmcnt(2)
	v_lshlrev_b32_e32 v36, 16, v54
	v_and_b32_e32 v37, 0xffff0000, v54
	s_waitcnt lgkmcnt(0)
	v_add_f32_e32 v0, v0, v3
	ds_bpermute_b32 v5, v47, v0
	v_lshlrev_b32_e32 v54, 16, v55
	v_and_b32_e32 v55, 0xffff0000, v55
	v_pk_fma_f32 v[60:61], v[212:213], v[36:37], v[60:61] neg_lo:[1,0,0] neg_hi:[1,0,0]
	v_pk_fma_f32 v[54:55], v[26:27], v[54:55], v[50:51]
	s_waitcnt lgkmcnt(0)
	v_add_f32_e32 v0, v0, v5
	ds_bpermute_b32 v68, v46, v0
	v_lshlrev_b32_e32 v36, 16, v52
	v_and_b32_e32 v37, 0xffff0000, v52
	v_lshlrev_b32_e32 v50, 16, v53
	v_and_b32_e32 v51, 0xffff0000, v53
	s_waitcnt lgkmcnt(0)
	v_add_f32_e32 v0, v0, v68
	ds_bpermute_b32 v68, v45, v0
	v_lshlrev_b32_e32 v52, 16, v56
	v_and_b32_e32 v53, 0xffff0000, v56
	v_lshlrev_b32_e32 v56, 16, v57
	v_and_b32_e32 v57, 0xffff0000, v57
	s_waitcnt lgkmcnt(0)
	v_add_f32_e32 v0, v0, v68
	v_pk_fma_f32 v[68:69], v[212:213], v[52:53], v[36:37] neg_lo:[1,0,0] neg_hi:[1,0,0]
	v_pk_fma_f32 v[70:71], v[26:27], v[56:57], v[50:51]
	v_pk_mul_f32 v[36:37], v[54:55], v[54:55]
	v_pk_mul_f32 v[50:51], v[60:61], v[60:61]
	v_fmamk_f32 v0, v0, 0x3c000000, v227
	v_pk_mov_b32 v[52:53], v[50:51], v[36:37] op_sel:[1,0]
	v_mov_b32_e32 v51, v37
	v_pk_add_f32 v[36:37], v[52:53], v[50:51]
	v_pk_mul_f32 v[50:51], v[70:71], v[70:71]
	v_pk_mul_f32 v[52:53], v[68:69], v[68:69]
	v_mov_b32_e32 v56, v50
	v_mov_b32_e32 v57, v52
	v_mov_b32_e32 v52, v51
	v_pk_add_f32 v[50:51], v[56:57], v[52:53]
	v_add_f32_e32 v36, v36, v37
	v_add_f32_e32 v36, v51, v36
	v_add_f32_e32 v56, v50, v36
	ds_bpermute_b32 v57, v48, v56
	v_rsq_f32_e32 v0, v0
	global_load_dwordx4 v[14:17], v[16:17], off sc1
	s_nop 0
	global_load_dwordx4 v[10:13], v[12:13], off sc1
	v_add_co_u32_e32 v2, vcc, s12, v6
	v_pk_mul_f32 v[50:51], v[64:65], v[0:1] op_sel_hi:[1,0]
	s_waitcnt lgkmcnt(0)
	v_add_f32_e32 v64, v56, v57
	ds_bpermute_b32 v65, v47, v64
	v_pk_mul_f32 v[52:53], v[66:67], v[0:1] op_sel_hi:[1,0]
	v_pk_mul_f32 v[56:57], v[58:59], v[0:1] op_sel_hi:[1,0]
	v_pk_mul_f32 v[58:59], v[62:63], v[0:1] op_sel_hi:[1,0]
	v_addc_co_u32_e32 v3, vcc, 0, v7, vcc
	s_waitcnt lgkmcnt(0)
	v_add_f32_e32 v0, v64, v65
	ds_bpermute_b32 v62, v46, v0
	v_pk_mul_f32 v[30:31], v[30:31], s[50:51] op_sel_hi:[1,0]
	v_pk_mul_f32 v[32:33], v[32:33], s[50:51] op_sel_hi:[1,0]
	v_add_co_u32_e32 v4, vcc, 0x7000, v6
	s_waitcnt lgkmcnt(0)
	v_add_f32_e32 v62, v0, v62
	ds_bpermute_b32 v63, v45, v62
	v_lshl_add_u64 v[36:37], s[10:11], 0, v[214:215]
	v_pk_mul_f32 v[52:53], v[34:35], v[52:53]
	v_pk_mul_f32 v[50:51], v[28:29], v[50:51]
	v_pk_mul_f32 v[58:59], v[32:33], v[58:59]
	v_pk_mul_f32 v[56:57], v[30:31], v[56:57]
	v_lshlrev_b32_e32 v0, 11, v99
	v_addc_co_u32_e32 v5, vcc, 0, v7, vcc
	v_cvt_pk_bf16_f32 v50, v50, v51
	v_cvt_pk_bf16_f32 v51, v52, v53
	v_cvt_pk_bf16_f32 v52, v56, v57
	v_cvt_pk_bf16_f32 v53, v58, v59
	v_lshl_add_u64 v[56:57], v[36:37], 0, v[0:1]
	s_waitcnt lgkmcnt(0)
	v_add_f32_e32 v0, v62, v63
	global_load_dwordx4 v[6:9], v[2:3], off sc1
	s_nop 0
	global_load_dwordx4 v[2:5], v[4:5], off sc1
	v_fmamk_f32 v0, v0, 0x3c000000, v227
	global_store_dwordx4 v[56:57], v[50:53], off
	v_rsq_f32_e32 v0, v0
	s_waitcnt vmcnt(6)
	v_lshlrev_b32_e32 v64, 16, v22
	v_lshl_add_u32 v50, v44, 8, v41
	ds_read_b128 v[50:53], v50
	v_pk_mul_f32 v[58:59], v[60:61], v[0:1] op_sel_hi:[1,0]
	v_pk_mul_f32 v[60:61], v[54:55], v[0:1] op_sel_hi:[1,0]
	v_lshl_add_u32 v54, v43, 8, v41
	ds_read_b128 v[54:57], v54
	s_waitcnt lgkmcnt(1)
	v_lshlrev_b32_e32 v62, 16, v50
	v_and_b32_e32 v63, 0xffff0000, v50
	v_lshlrev_b32_e32 v50, 16, v51
	v_and_b32_e32 v51, 0xffff0000, v51
	v_and_b32_e32 v65, 0xffff0000, v22
	v_lshlrev_b32_e32 v22, 16, v23
	v_and_b32_e32 v23, 0xffff0000, v23
	v_pk_fma_f32 v[62:63], v[212:213], v[64:65], v[62:63] neg_lo:[1,0,0] neg_hi:[1,0,0]
	v_pk_fma_f32 v[50:51], v[26:27], v[22:23], v[50:51]
	v_lshlrev_b32_e32 v22, 16, v52
	v_and_b32_e32 v23, 0xffff0000, v52
	v_lshlrev_b32_e32 v52, 16, v53
	v_and_b32_e32 v53, 0xffff0000, v53
	v_lshlrev_b32_e32 v64, 16, v24
	v_and_b32_e32 v65, 0xffff0000, v24
	v_lshlrev_b32_e32 v24, 16, v25
	v_and_b32_e32 v25, 0xffff0000, v25
	v_pk_fma_f32 v[64:65], v[212:213], v[64:65], v[22:23] neg_lo:[1,0,0] neg_hi:[1,0,0]
	v_pk_fma_f32 v[52:53], v[26:27], v[24:25], v[52:53]
	v_pk_mul_f32 v[22:23], v[50:51], v[50:51]
	v_pk_mul_f32 v[24:25], v[62:63], v[62:63]
	s_nop 0
	v_pk_mov_b32 v[66:67], v[24:25], v[22:23] op_sel:[1,0]
	v_mov_b32_e32 v25, v23
	v_pk_add_f32 v[22:23], v[66:67], v[24:25]
	v_pk_mul_f32 v[24:25], v[52:53], v[52:53]
	v_pk_mul_f32 v[66:67], v[64:65], v[64:65]
	v_mov_b32_e32 v72, v24
	v_mov_b32_e32 v73, v66
	v_mov_b32_e32 v66, v25
	v_pk_add_f32 v[24:25], v[72:73], v[66:67]
	v_add_f32_e32 v22, v22, v23
	v_add_f32_e32 v22, v25, v22
	v_add_f32_e32 v66, v24, v22
	ds_bpermute_b32 v67, v48, v66
	v_pk_mul_f32 v[24:25], v[34:35], v[60:61]
	v_pk_mul_f32 v[22:23], v[28:29], v[58:59]
	v_pk_mul_f32 v[58:59], v[68:69], v[0:1] op_sel_hi:[1,0]
	v_pk_mul_f32 v[60:61], v[70:71], v[0:1] op_sel_hi:[1,0]
	s_waitcnt lgkmcnt(0)
	v_add_f32_e32 v0, v66, v67
	ds_bpermute_b32 v66, v47, v0
	v_pk_mul_f32 v[60:61], v[32:33], v[60:61]
	v_pk_mul_f32 v[58:59], v[30:31], v[58:59]
	v_cvt_pk_bf16_f32 v22, v22, v23
	v_cvt_pk_bf16_f32 v23, v24, v25
	s_waitcnt lgkmcnt(0)
	v_add_f32_e32 v66, v0, v66
	ds_bpermute_b32 v67, v46, v66
	v_lshlrev_b32_e32 v0, 11, v49
	v_cvt_pk_bf16_f32 v24, v58, v59
	v_cvt_pk_bf16_f32 v25, v60, v61
	v_lshl_add_u64 v[58:59], v[36:37], 0, v[0:1]
	s_waitcnt lgkmcnt(0)
	v_add_f32_e32 v0, v66, v67
	v_lshlrev_b32_e32 v60, 16, v54
	v_and_b32_e32 v61, 0xffff0000, v54
	v_lshlrev_b32_e32 v54, 16, v55
	v_and_b32_e32 v55, 0xffff0000, v55
	s_waitcnt vmcnt(5)
	v_lshlrev_b32_e32 v66, 16, v18
	v_and_b32_e32 v67, 0xffff0000, v18
	v_lshlrev_b32_e32 v18, 16, v19
	v_and_b32_e32 v19, 0xffff0000, v19
	v_pk_fma_f32 v[60:61], v[212:213], v[66:67], v[60:61] neg_lo:[1,0,0] neg_hi:[1,0,0]
	v_pk_fma_f32 v[54:55], v[26:27], v[18:19], v[54:55]
	v_lshlrev_b32_e32 v18, 16, v56
	v_and_b32_e32 v19, 0xffff0000, v56
	v_lshlrev_b32_e32 v56, 16, v57
	v_and_b32_e32 v57, 0xffff0000, v57
	v_lshlrev_b32_e32 v66, 16, v20
	v_and_b32_e32 v67, 0xffff0000, v20
	v_lshlrev_b32_e32 v20, 16, v21
	v_and_b32_e32 v21, 0xffff0000, v21
	v_pk_fma_f32 v[66:67], v[212:213], v[66:67], v[18:19] neg_lo:[1,0,0] neg_hi:[1,0,0]
	v_pk_fma_f32 v[56:57], v[26:27], v[20:21], v[56:57]
	v_pk_mul_f32 v[18:19], v[54:55], v[54:55]
	v_pk_mul_f32 v[20:21], v[60:61], v[60:61]
	ds_bpermute_b32 v49, v45, v0
	v_pk_mov_b32 v[68:69], v[20:21], v[18:19] op_sel:[1,0]
	v_mov_b32_e32 v21, v19
	v_pk_add_f32 v[18:19], v[68:69], v[20:21]
	v_pk_mul_f32 v[20:21], v[56:57], v[56:57]
	v_pk_mul_f32 v[68:69], v[66:67], v[66:67]
	v_mov_b32_e32 v70, v20
	v_mov_b32_e32 v71, v68
	v_mov_b32_e32 v68, v21
	v_pk_add_f32 v[20:21], v[70:71], v[68:69]
	v_add_f32_e32 v18, v18, v19
	v_add_f32_e32 v18, v21, v18
	v_add_f32_e32 v18, v20, v18
	ds_bpermute_b32 v19, v48, v18
	global_store_dwordx4 v[58:59], v[22:25], off
	s_waitcnt lgkmcnt(1)
	v_add_f32_e32 v0, v0, v49
	v_fmamk_f32 v0, v0, 0x3c000000, v227
	v_rsq_f32_e32 v0, v0
	s_waitcnt lgkmcnt(0)
	v_add_f32_e32 v22, v18, v19
	ds_bpermute_b32 v23, v47, v22
	v_pk_mul_f32 v[20:21], v[50:51], v[0:1] op_sel_hi:[1,0]
	v_pk_mul_f32 v[18:19], v[62:63], v[0:1] op_sel_hi:[1,0]
	v_pk_mul_f32 v[24:25], v[52:53], v[0:1] op_sel_hi:[1,0]
	s_waitcnt lgkmcnt(0)
	v_add_f32_e32 v49, v22, v23
	ds_bpermute_b32 v50, v46, v49
	v_pk_mul_f32 v[22:23], v[64:65], v[0:1] op_sel_hi:[1,0]
	v_pk_mul_f32 v[20:21], v[34:35], v[20:21]
	v_pk_mul_f32 v[18:19], v[28:29], v[18:19]
	v_pk_mul_f32 v[22:23], v[30:31], v[22:23]
	s_waitcnt lgkmcnt(0)
	v_add_f32_e32 v0, v49, v50
	ds_bpermute_b32 v49, v45, v0
	v_pk_mul_f32 v[24:25], v[32:33], v[24:25]
	v_cvt_pk_bf16_f32 v18, v18, v19
	v_cvt_pk_bf16_f32 v19, v20, v21
	v_cvt_pk_bf16_f32 v20, v22, v23
	v_lshl_add_u32 v22, v42, 8, v41
	v_cvt_pk_bf16_f32 v21, v24, v25
	ds_read_b128 v[22:25], v22
	s_waitcnt lgkmcnt(1)
	v_add_f32_e32 v0, v0, v49
	v_fmamk_f32 v0, v0, 0x3c000000, v227
	v_rsq_f32_e32 v58, v0
	v_lshl_add_u32 v0, v40, 8, v41
	ds_read_b128 v[50:53], v0
	s_waitcnt lgkmcnt(1)
	v_lshlrev_b32_e32 v62, 16, v22
	v_and_b32_e32 v63, 0xffff0000, v22
	v_lshlrev_b32_e32 v22, 16, v23
	v_and_b32_e32 v23, 0xffff0000, v23
	s_waitcnt vmcnt(5)
	v_lshlrev_b32_e32 v64, 16, v14
	v_and_b32_e32 v65, 0xffff0000, v14
	v_lshlrev_b32_e32 v14, 16, v15
	v_and_b32_e32 v15, 0xffff0000, v15
	v_pk_fma_f32 v[62:63], v[212:213], v[64:65], v[62:63] neg_lo:[1,0,0] neg_hi:[1,0,0]
	v_pk_fma_f32 v[22:23], v[26:27], v[14:15], v[22:23]
	v_lshlrev_b32_e32 v14, 16, v24
	v_and_b32_e32 v15, 0xffff0000, v24
	v_lshlrev_b32_e32 v24, 16, v25
	v_and_b32_e32 v25, 0xffff0000, v25
	v_lshlrev_b32_e32 v64, 16, v16
	v_and_b32_e32 v65, 0xffff0000, v16
	v_lshlrev_b32_e32 v16, 16, v17
	v_and_b32_e32 v17, 0xffff0000, v17
	v_pk_fma_f32 v[64:65], v[212:213], v[64:65], v[14:15] neg_lo:[1,0,0] neg_hi:[1,0,0]
	v_pk_fma_f32 v[24:25], v[26:27], v[16:17], v[24:25]
	v_pk_mul_f32 v[14:15], v[22:23], v[22:23]
	v_pk_mul_f32 v[16:17], v[62:63], v[62:63]
	s_nop 0
	v_pk_mov_b32 v[68:69], v[16:17], v[14:15] op_sel:[1,0]
	v_mov_b32_e32 v17, v15
	v_pk_add_f32 v[14:15], v[68:69], v[16:17]
	v_pk_mul_f32 v[16:17], v[24:25], v[24:25]
	v_pk_mul_f32 v[68:69], v[64:65], v[64:65]
	v_mov_b32_e32 v70, v16
	v_mov_b32_e32 v71, v68
	v_mov_b32_e32 v68, v17
	v_pk_add_f32 v[16:17], v[70:71], v[68:69]
	v_add_f32_e32 v0, v14, v15
	v_add_f32_e32 v0, v17, v0
	v_add_f32_e32 v16, v16, v0
	ds_bpermute_b32 v17, v48, v16
	v_lshlrev_b32_e32 v0, 11, v44
	v_lshl_add_u64 v[14:15], v[36:37], 0, v[0:1]
	global_store_dwordx4 v[14:15], v[18:21], off
	v_pk_mul_f32 v[14:15], v[60:61], v[58:59] op_sel_hi:[1,0]
	s_waitcnt lgkmcnt(0)
	v_add_f32_e32 v0, v16, v17
	ds_bpermute_b32 v20, v47, v0
	v_pk_mul_f32 v[16:17], v[54:55], v[58:59] op_sel_hi:[1,0]
	v_pk_mul_f32 v[14:15], v[28:29], v[14:15]
	v_pk_mul_f32 v[16:17], v[34:35], v[16:17]
	v_cvt_pk_bf16_f32 v14, v14, v15
	s_waitcnt lgkmcnt(0)
	v_add_f32_e32 v0, v0, v20
	ds_bpermute_b32 v44, v46, v0
	v_pk_mul_f32 v[20:21], v[56:57], v[58:59] op_sel_hi:[1,0]
	v_cvt_pk_bf16_f32 v15, v16, v17
	v_pk_mul_f32 v[20:21], v[32:33], v[20:21]
	s_waitcnt vmcnt(5)
	v_lshlrev_b32_e32 v54, 16, v10
	v_cvt_pk_bf16_f32 v17, v20, v21
	v_lshlrev_b32_e32 v20, 16, v50
	v_and_b32_e32 v21, 0xffff0000, v50
	v_lshlrev_b32_e32 v50, 16, v51
	v_and_b32_e32 v51, 0xffff0000, v51
	v_and_b32_e32 v55, 0xffff0000, v10
	v_lshlrev_b32_e32 v10, 16, v11
	v_and_b32_e32 v11, 0xffff0000, v11
	v_pk_fma_f32 v[20:21], v[212:213], v[54:55], v[20:21] neg_lo:[1,0,0] neg_hi:[1,0,0]
	v_pk_fma_f32 v[50:51], v[26:27], v[10:11], v[50:51]
	v_lshlrev_b32_e32 v10, 16, v52
	v_and_b32_e32 v11, 0xffff0000, v52
	v_lshlrev_b32_e32 v52, 16, v53
	v_and_b32_e32 v53, 0xffff0000, v53
	v_lshlrev_b32_e32 v54, 16, v12
	v_and_b32_e32 v55, 0xffff0000, v12
	v_lshlrev_b32_e32 v12, 16, v13
	v_and_b32_e32 v13, 0xffff0000, v13
	v_pk_fma_f32 v[54:55], v[212:213], v[54:55], v[10:11] neg_lo:[1,0,0] neg_hi:[1,0,0]
	v_pk_fma_f32 v[52:53], v[26:27], v[12:13], v[52:53]
	v_pk_mul_f32 v[10:11], v[50:51], v[50:51]
	v_pk_mul_f32 v[12:13], v[20:21], v[20:21]
	s_waitcnt lgkmcnt(0)
	v_add_f32_e32 v44, v0, v44
	v_pk_mov_b32 v[56:57], v[12:13], v[10:11] op_sel:[1,0]
	v_mov_b32_e32 v13, v11
	ds_bpermute_b32 v49, v45, v44
	v_pk_add_f32 v[10:11], v[56:57], v[12:13]
	v_pk_mul_f32 v[12:13], v[52:53], v[52:53]
	v_pk_mul_f32 v[56:57], v[54:55], v[54:55]
	v_pk_mul_f32 v[18:19], v[66:67], v[58:59] op_sel_hi:[1,0]
	v_mov_b32_e32 v58, v12
	v_mov_b32_e32 v59, v56
	v_mov_b32_e32 v56, v13
	v_pk_add_f32 v[12:13], v[58:59], v[56:57]
	v_add_f32_e32 v10, v10, v11
	v_pk_mul_f32 v[18:19], v[30:31], v[18:19]
	v_add_f32_e32 v10, v13, v10
	v_cvt_pk_bf16_f32 v16, v18, v19
	v_add_f32_e32 v19, v12, v10
	v_lshlrev_b32_e32 v0, 11, v43
	s_waitcnt lgkmcnt(0)
	v_add_f32_e32 v18, v44, v49
	ds_bpermute_b32 v43, v48, v19
	v_fmamk_f32 v18, v18, 0x3c000000, v227
	v_rsq_f32_e32 v18, v18
	v_lshl_add_u64 v[10:11], v[36:37], 0, v[0:1]
	global_store_dwordx4 v[10:11], v[14:17], off
	s_waitcnt lgkmcnt(0)
	v_add_f32_e32 v0, v19, v43
	v_pk_mul_f32 v[10:11], v[62:63], v[18:19] op_sel_hi:[1,0]
	v_pk_mul_f32 v[12:13], v[22:23], v[18:19] op_sel_hi:[1,0]
	ds_bpermute_b32 v19, v47, v0
	v_pk_mul_f32 v[12:13], v[34:35], v[12:13]
	v_pk_mul_f32 v[10:11], v[28:29], v[10:11]
	s_waitcnt lgkmcnt(0)
	v_add_f32_e32 v0, v0, v19
	v_pk_mul_f32 v[14:15], v[64:65], v[18:19] op_sel_hi:[1,0]
	v_pk_mul_f32 v[16:17], v[24:25], v[18:19] op_sel_hi:[1,0]
	ds_bpermute_b32 v18, v46, v0
	v_pk_mul_f32 v[16:17], v[32:33], v[16:17]
	v_pk_mul_f32 v[14:15], v[30:31], v[14:15]
	v_cvt_pk_bf16_f32 v10, v10, v11
	v_cvt_pk_bf16_f32 v11, v12, v13
	s_waitcnt lgkmcnt(0)
	v_add_f32_e32 v18, v0, v18
	v_lshlrev_b32_e32 v0, 11, v42
	v_cvt_pk_bf16_f32 v12, v14, v15
	v_cvt_pk_bf16_f32 v13, v16, v17
	v_lshl_add_u64 v[14:15], v[36:37], 0, v[0:1]
	ds_bpermute_b32 v19, v45, v18
	global_store_dwordx4 v[14:15], v[10:13], off
	v_lshl_add_u32 v14, v38, 8, v41
	ds_read_b128 v[14:17], v14
	v_lshl_add_u32 v10, v39, 8, v41
	ds_read_b128 v[10:13], v10
	s_waitcnt lgkmcnt(2)
	v_add_f32_e32 v0, v18, v19
	v_fmamk_f32 v0, v0, 0x3c000000, v227
	s_waitcnt vmcnt(6)
	v_lshlrev_b32_e32 v24, 16, v6
	v_and_b32_e32 v25, 0xffff0000, v6
	s_waitcnt lgkmcnt(0)
	v_lshlrev_b32_e32 v22, 16, v10
	v_and_b32_e32 v23, 0xffff0000, v10
	v_lshlrev_b32_e32 v10, 16, v11
	v_and_b32_e32 v11, 0xffff0000, v11
	v_lshlrev_b32_e32 v6, 16, v7
	v_and_b32_e32 v7, 0xffff0000, v7
	v_rsq_f32_e32 v0, v0
	v_pk_fma_f32 v[22:23], v[212:213], v[24:25], v[22:23] neg_lo:[1,0,0] neg_hi:[1,0,0]
	v_pk_fma_f32 v[10:11], v[26:27], v[6:7], v[10:11]
	v_lshlrev_b32_e32 v6, 16, v12
	v_and_b32_e32 v7, 0xffff0000, v12
	v_lshlrev_b32_e32 v12, 16, v13
	v_and_b32_e32 v13, 0xffff0000, v13
	v_lshlrev_b32_e32 v24, 16, v8
	v_and_b32_e32 v25, 0xffff0000, v8
	v_lshlrev_b32_e32 v8, 16, v9
	v_and_b32_e32 v9, 0xffff0000, v9
	v_pk_fma_f32 v[24:25], v[212:213], v[24:25], v[6:7] neg_lo:[1,0,0] neg_hi:[1,0,0]
	v_pk_fma_f32 v[12:13], v[26:27], v[8:9], v[12:13]
	v_pk_mul_f32 v[6:7], v[10:11], v[10:11]
	v_pk_mul_f32 v[8:9], v[22:23], v[22:23]
	v_pk_mul_f32 v[18:19], v[20:21], v[0:1] op_sel_hi:[1,0]
	v_pk_mov_b32 v[42:43], v[8:9], v[6:7] op_sel:[1,0]
	v_mov_b32_e32 v9, v7
	v_pk_add_f32 v[6:7], v[42:43], v[8:9]
	v_pk_mul_f32 v[8:9], v[12:13], v[12:13]
	v_pk_mul_f32 v[42:43], v[24:25], v[24:25]
	v_pk_mul_f32 v[20:21], v[50:51], v[0:1] op_sel_hi:[1,0]
	v_mov_b32_e32 v50, v8
	v_mov_b32_e32 v51, v42
	v_mov_b32_e32 v42, v9
	v_pk_add_f32 v[8:9], v[50:51], v[42:43]
	v_add_f32_e32 v6, v6, v7
	v_add_f32_e32 v6, v9, v6
	v_add_f32_e32 v41, v8, v6
	ds_bpermute_b32 v42, v48, v41
	v_pk_mul_f32 v[8:9], v[34:35], v[20:21]
	v_pk_mul_f32 v[6:7], v[28:29], v[18:19]
	v_pk_mul_f32 v[18:19], v[54:55], v[0:1] op_sel_hi:[1,0]
	v_pk_mul_f32 v[20:21], v[52:53], v[0:1] op_sel_hi:[1,0]
	s_waitcnt lgkmcnt(0)
	v_add_f32_e32 v0, v41, v42
	ds_bpermute_b32 v41, v47, v0
	v_pk_mul_f32 v[20:21], v[32:33], v[20:21]
	v_pk_mul_f32 v[18:19], v[30:31], v[18:19]
	v_cvt_pk_bf16_f32 v6, v6, v7
	v_cvt_pk_bf16_f32 v7, v8, v9
	s_waitcnt lgkmcnt(0)
	v_add_f32_e32 v41, v0, v41
	ds_bpermute_b32 v42, v46, v41
	v_lshlrev_b32_e32 v0, 11, v40
	v_cvt_pk_bf16_f32 v8, v18, v19
	v_cvt_pk_bf16_f32 v9, v20, v21
	v_lshl_add_u64 v[18:19], v[36:37], 0, v[0:1]
	s_waitcnt lgkmcnt(0)
	v_add_f32_e32 v0, v41, v42
	v_lshlrev_b32_e32 v20, 16, v14
	v_and_b32_e32 v21, 0xffff0000, v14
	v_lshlrev_b32_e32 v14, 16, v15
	v_and_b32_e32 v15, 0xffff0000, v15
	s_waitcnt vmcnt(5)
	v_lshlrev_b32_e32 v40, 16, v2
	v_and_b32_e32 v41, 0xffff0000, v2
	v_lshlrev_b32_e32 v2, 16, v3
	v_and_b32_e32 v3, 0xffff0000, v3
	v_pk_fma_f32 v[20:21], v[212:213], v[40:41], v[20:21] neg_lo:[1,0,0] neg_hi:[1,0,0]
	v_pk_fma_f32 v[14:15], v[26:27], v[2:3], v[14:15]
	v_lshlrev_b32_e32 v2, 16, v16
	v_and_b32_e32 v3, 0xffff0000, v16
	v_lshlrev_b32_e32 v16, 16, v17
	v_and_b32_e32 v17, 0xffff0000, v17
	v_lshlrev_b32_e32 v40, 16, v4
	v_and_b32_e32 v41, 0xffff0000, v4
	v_lshlrev_b32_e32 v4, 16, v5
	v_and_b32_e32 v5, 0xffff0000, v5
	v_pk_fma_f32 v[40:41], v[212:213], v[40:41], v[2:3] neg_lo:[1,0,0] neg_hi:[1,0,0]
	v_pk_fma_f32 v[16:17], v[26:27], v[4:5], v[16:17]
	v_pk_mul_f32 v[2:3], v[14:15], v[14:15]
	v_pk_mul_f32 v[4:5], v[20:21], v[20:21]
	ds_bpermute_b32 v44, v45, v0
	v_pk_mov_b32 v[26:27], v[4:5], v[2:3] op_sel:[1,0]
	v_mov_b32_e32 v5, v3
	v_pk_add_f32 v[2:3], v[26:27], v[4:5]
	v_pk_mul_f32 v[4:5], v[16:17], v[16:17]
	v_pk_mul_f32 v[26:27], v[40:41], v[40:41]
	v_mov_b32_e32 v42, v4
	v_mov_b32_e32 v43, v26
	v_mov_b32_e32 v26, v5
	v_pk_add_f32 v[4:5], v[42:43], v[26:27]
	v_add_f32_e32 v2, v2, v3
	v_add_f32_e32 v2, v5, v2
	v_add_f32_e32 v2, v4, v2
	ds_bpermute_b32 v3, v48, v2
	s_waitcnt lgkmcnt(1)
	v_add_f32_e32 v0, v0, v44
	global_store_dwordx4 v[18:19], v[6:9], off
	v_fmamk_f32 v0, v0, 0x3c000000, v227
	v_rsq_f32_e32 v0, v0
	s_waitcnt lgkmcnt(0)
	v_add_f32_e32 v6, v2, v3
	ds_bpermute_b32 v7, v47, v6
	v_pk_mul_f32 v[4:5], v[10:11], v[0:1] op_sel_hi:[1,0]
	v_pk_mul_f32 v[2:3], v[22:23], v[0:1] op_sel_hi:[1,0]
	v_pk_mul_f32 v[8:9], v[12:13], v[0:1] op_sel_hi:[1,0]
	s_waitcnt lgkmcnt(0)
	v_add_f32_e32 v10, v6, v7
	ds_bpermute_b32 v11, v46, v10
	v_pk_mul_f32 v[6:7], v[24:25], v[0:1] op_sel_hi:[1,0]
	v_pk_mul_f32 v[4:5], v[34:35], v[4:5]
	v_pk_mul_f32 v[2:3], v[28:29], v[2:3]
	v_pk_mul_f32 v[6:7], v[30:31], v[6:7]
	s_waitcnt lgkmcnt(0)
	v_add_f32_e32 v0, v10, v11
	ds_bpermute_b32 v10, v45, v0
	v_cvt_pk_bf16_f32 v2, v2, v3
	v_cvt_pk_bf16_f32 v3, v4, v5
	v_cvt_pk_bf16_f32 v4, v6, v7
	v_pk_mul_f32 v[8:9], v[32:33], v[8:9]
	s_waitcnt lgkmcnt(0)
	v_add_f32_e32 v0, v0, v10
	v_fmamk_f32 v0, v0, 0x3c000000, v227
	v_rsq_f32_e32 v6, v0
	v_lshlrev_b32_e32 v0, 11, v39
	v_cvt_pk_bf16_f32 v5, v8, v9
	v_lshl_add_u64 v[8:9], v[36:37], 0, v[0:1]
	global_store_dwordx4 v[8:9], v[2:5], off
	v_pk_mul_f32 v[8:9], v[40:41], v[6:7] op_sel_hi:[1,0]
	v_lshlrev_b32_e32 v0, 11, v38
	v_pk_mul_f32 v[2:3], v[20:21], v[6:7] op_sel_hi:[1,0]
	v_pk_mul_f32 v[4:5], v[14:15], v[6:7] op_sel_hi:[1,0]
	v_pk_mul_f32 v[6:7], v[16:17], v[6:7] op_sel_hi:[1,0]
	v_pk_mul_f32 v[4:5], v[34:35], v[4:5]
	v_pk_mul_f32 v[2:3], v[28:29], v[2:3]
	v_pk_mul_f32 v[6:7], v[32:33], v[6:7]
	v_pk_mul_f32 v[8:9], v[30:31], v[8:9]
	v_cvt_pk_bf16_f32 v2, v2, v3
	v_cvt_pk_bf16_f32 v3, v4, v5
	v_cvt_pk_bf16_f32 v4, v8, v9
	v_cvt_pk_bf16_f32 v5, v6, v7
	v_lshl_add_u64 v[6:7], v[36:37], 0, v[0:1]
	global_store_dwordx4 v[6:7], v[2:5], off
	s_waitcnt lgkmcnt(0)
	s_barrier
